# layer-0 FFN weight transposes moved from the in_proj phase's side jobs to the 160 workgroups idle during the GLU GEMM phase (same loop code via trampoline)
# speedup vs baseline: 1.0084x; 1.0032x over previous
.LBB0_800:
	s_lshr_b32 s34, s42, 1
	s_cmp_lt_i32 s2, s34
	s_cbranch_scc1 .LBB0_925
	s_sub_i32 s45, s42, s34
	s_sub_i32 s28, s2, s34
	s_branch .LBB0_824
.Lp6_tr:
	s_mov_b64 s[16:17], s[0:1]
	s_load_dwordx2 s[18:19], s[0:1], 0xe8
	s_sub_i32 s28, s2, 0x60
	s_movk_i32 s45, 0xa0
	s_waitcnt lgkmcnt(0)
	s_add_u32 s20, s18, 0x7bc000
	s_addc_u32 s21, s19, 0
	v_mov_b32_e32 v0, v170
	s_cmpk_gt_i32 s28, 0x1ff
	s_cbranch_scc1 .Lp6_ret
	v_add_u32_e32 v3, 0x200, v0
	v_ashrrev_i32_e32 v5, 6, v3
	v_add_u32_e32 v3, 0x400, v0
	v_ashrrev_i32_e32 v6, 6, v3
	v_add_u32_e32 v3, 0x600, v0
	v_ashrrev_i32_e32 v7, 6, v3
	v_add_u32_e32 v3, 0x800, v0
	v_ashrrev_i32_e32 v8, 6, v3
	v_add_u32_e32 v3, 0xa00, v0
	s_add_u32 s4, s18, 0x1ebc000
	v_ashrrev_i32_e32 v9, 6, v3
	v_add_u32_e32 v3, 0xc00, v0
	s_addc_u32 s5, s19, 0
	v_ashrrev_i32_e32 v10, 6, v3
	v_add_u32_e32 v3, 0xe00, v0
	s_add_u32 s29, s18, 0xebc000
	v_ashrrev_i32_e32 v11, 6, v3
	v_bfe_u32 v3, v0, 4, 2
	v_lshlrev_b32_e32 v12, 4, v0
	s_addc_u32 s30, s19, 0
	v_mul_u32_u24_e32 v3, 0x4100, v3
	v_and_b32_e32 v12, 0xf0, v12
	s_add_u32 s31, s18, 0xe3c000
	v_lshlrev_b32_e32 v1, 2, v0
	v_ashrrev_i32_e32 v4, 6, v0
	v_add3_u32 v3, 0, v3, v12
	v_ashrrev_i32_e32 v12, 3, v0
	v_lshlrev_b32_e32 v0, 3, v0
	s_addc_u32 s35, s19, 0
	v_and_b32_e32 v24, 56, v0
	s_add_u32 s6, s18, 0xdbc000
	v_mul_u32_u24_e32 v0, 0x41, v24
	s_addc_u32 s7, s19, 0
	s_movk_i32 s10, 0x104
	v_lshlrev_b32_e32 v14, 2, v12
	v_lshlrev_b32_e32 v0, 2, v0
	s_add_u32 s8, s18, 0xbbc000
	v_and_b32_e32 v2, 0xfc, v1
	v_mov_b32_e32 v1, 0
	v_mul_lo_u32 v15, v4, s10
	v_mul_lo_u32 v16, v5, s10
	v_mul_lo_u32 v17, v6, s10
	v_mul_lo_u32 v18, v7, s10
	v_mul_lo_u32 v19, v8, s10
	v_mul_lo_u32 v20, v9, s10
	v_mul_lo_u32 v21, v10, s10
	v_mul_lo_u32 v22, v11, s10
	v_add3_u32 v13, 0, v14, v0
	v_add3_u32 v14, 0, v0, v14
	s_addc_u32 s9, s19, 0
	s_mov_b32 s11, 0
	s_movk_i32 s36, 0xe0
	v_lshlrev_b32_e32 v0, 2, v2
	v_add_u32_e32 v15, v3, v15
	v_add_u32_e32 v16, v3, v16
	v_add_u32_e32 v17, v3, v17
	v_add_u32_e32 v18, v3, v18
	v_add_u32_e32 v19, v3, v19
	v_add_u32_e32 v20, v3, v20
	v_add_u32_e32 v21, v3, v21
	v_add_u32_e32 v22, v3, v22
	v_lshlrev_b32_e32 v2, 1, v24
	v_mov_b32_e32 v3, v1
	v_add_u32_e32 v23, 0x400, v13
	v_add_u32_e32 v24, 0x400, v14
	v_add_u32_e32 v25, 0x4000, v13
	v_add_u32_e32 v26, 0x4200, v14
	v_add_u32_e32 v27, 0x4400, v13
	v_add_u32_e32 v28, 0x4600, v14
	v_add_u32_e32 v29, 0x8200, v13
	v_add_u32_e32 v30, 0x8200, v14
	v_add_u32_e32 v31, 0x8600, v13
	v_add_u32_e32 v32, 0x8600, v14
	v_add_u32_e32 v33, 0xc200, v13
	v_add_u32_e32 v34, 0xc400, v14
	v_add_u32_e32 v35, 0xc600, v13
	v_add_u32_e32 v36, 0xc800, v14
	s_mov_b32 s37, s28
	s_branch .LBB0_804

.Lp6_ret:
	s_mov_b64 exec, -1
	s_branch .LBB0_1182
